# v28 plus GQA unit prologue: gate rows touched early, q-norm weights preloaded into spare registers
# baseline (speedup 1.0000x reference)
.LBB0_496:
	v_readlane_b32 s4, v254, 33
	v_readlane_b32 s5, v254, 34
	s_mov_b64 s[0:1], -1
	s_and_b64 vcc, exec, s[4:5]
	s_mul_i32 s23, s28, 0x88
	s_cbranch_vccz .LBB0_517
	s_mov_b32 s0, s92
	v_mbcnt_lo_u32_b32 v74, -1, 0
	v_mbcnt_hi_u32_b32 v74, -1, v74
	s_lshl_b32 s48, s28, 1
	v_and_b32_e32 v132, 31, v74
	v_or_b32_e32 v75, s0, v132
	v_bfe_u32 v131, v74, 5, 1
	v_mad_u64_u32 v[0:1], s[0:1], v75, s28, 0
	v_lshl_add_u64 v[0:1], v[0:1], 1, s[56:57]
	v_lshlrev_b32_e32 v160, 4, v131
	v_lshl_add_u64 v[4:5], v[0:1], 0, v[160:161]
	s_cmp_lg_u64 s[62:63], 0
	s_cbranch_scc0 .Lattn_gtouch_skip
	v_lshrrev_b32_e32 v32, 1, v74
	v_or_b32_e32 v32, s92, v32
	v_mul_lo_u32 v32, v32, s50
	v_and_b32_e32 v33, 1, v74
	v_lshlrev_b32_e32 v32, 1, v32
	v_lshl_add_u32 v32, v33, 7, v32
	global_load_dword v24, v32, s[62:63]
.Lattn_gtouch_skip:
	s_cmp_lg_u64 s[10:11], 0
	s_cbranch_scc0 .Lattn_qwpre_skip
	v_lshrrev_b32_e32 v32, 5, v74
	v_lshlrev_b32_e32 v32, 5, v32
	global_load_dwordx4 v[180:183], v32, s[10:11] offset:80
	global_load_dwordx4 v[184:187], v32, s[10:11] offset:64
	global_load_dwordx4 v[188:191], v32, s[10:11] offset:16
	global_load_dwordx4 v[192:195], v32, s[10:11]
	global_load_dwordx4 v[196:199], v32, s[10:11] offset:144
	global_load_dwordx4 v[200:203], v32, s[10:11] offset:128
	global_load_dwordx4 v[208:211], v32, s[10:11] offset:208
	global_load_dwordx4 v[216:219], v32, s[10:11] offset:192
	global_load_dwordx4 v[220:223], v32, s[10:11] offset:336
	global_load_dwordx4 v[224:227], v32, s[10:11] offset:320
	global_load_dwordx4 v[228:231], v32, s[10:11] offset:272
	global_load_dwordx4 v[232:235], v32, s[10:11] offset:256
	global_load_dwordx4 v[236:239], v32, s[10:11] offset:400
	global_load_dwordx4 v[240:243], v32, s[10:11] offset:384
	global_load_dwordx4 v[244:247], v32, s[10:11] offset:464
	global_load_dwordx4 v[248:251], v32, s[10:11] offset:448
.Lattn_qwpre_skip:
	global_load_dwordx4 v[24:27], v[4:5], off
	global_load_dwordx4 v[16:19], v[4:5], off offset:32
	global_load_dwordx4 v[28:31], v[4:5], off offset:64
	global_load_dwordx4 v[20:23], v[4:5], off offset:96
	global_load_dwordx4 v[8:11], v[4:5], off offset:128
	global_load_dwordx4 v[0:3], v[4:5], off offset:160
	global_load_dwordx4 v[12:15], v[4:5], off offset:192
	s_nop 0
	global_load_dwordx4 v[4:7], v[4:5], off offset:224
	v_bfe_u32 v69, v74, 4, 2
	v_readlane_b32 s0, v253, 3
	v_and_b32_e32 v73, 15, v74
	v_readlane_b32 s1, v253, 4
	v_or_b32_e32 v32, s0, v69
	v_lshlrev_b32_e32 v35, 4, v74
	v_bitop3_b32 v33, v69, v73, s1 bitop3:0x36
	v_lshlrev_b32_e32 v33, 4, v33
	v_bfe_u32 v72, v74, 2, 3
	v_and_b32_e32 v35, 48, v35
	v_mul_lo_u32 v32, v32, s48
	v_or_b32_e32 v34, s0, v72
	v_lshl_or_b32 v133, v131, 6, v35
	s_and_b32 s37, s91, 0xffff
	s_mov_b32 s36, s90
	v_or_b32_e32 v35, v33, v32
	v_readlane_b32 s1, v253, 6
	s_mov_b32 s0, m0
	s_mov_b32 m0, s1
	s_nop 0
	buffer_load_dwordx4 v35, s[36:39], s49 offen lds
	s_mov_b32 m0, s0
	s_lshl_b32 s0, s28, 3
	v_bitop3_b32 v32, v33, 64, v32 bitop3:0x36
	v_readlane_b32 s4, v253, 8
	s_mov_b32 s1, m0
	s_mov_b32 m0, s4
	s_nop 0
	buffer_load_dwordx4 v32, s[36:39], s0 offen lds
	s_mov_b32 m0, s1
	s_and_b32 s0, s41, 0xffff
	s_mov_b64 s[12:13], s[36:37]
	v_mul_lo_u32 v33, v34, s48
	s_mov_b64 s[14:15], s[38:39]
	s_mov_b32 s12, s40
	s_mov_b32 s13, s0
	v_or_b32_e32 v33, v33, v133
	v_readlane_b32 s1, v253, 7
	s_mov_b32 s0, m0
	s_mov_b32 m0, s1
	s_nop 0
	buffer_load_dwordx4 v33, s[12:15], s49 offen lds
	s_mov_b32 m0, s0
	v_or_b32_e32 v34, 0x80, v33
	v_readlane_b32 s1, v253, 9
	s_mov_b32 s0, m0
	s_mov_b32 m0, s1
	s_nop 0
	buffer_load_dwordx4 v34, s[12:15], s49 offen lds
	s_mov_b32 m0, s0
	s_mov_b32 s17, s93
	s_mov_b32 s93, s60
	s_mov_b32 s60, s72
	s_lshl_b32 s72, s28, 7
	v_readlane_b32 s1, v253, 10
	s_mov_b32 s0, m0
	s_mov_b32 m0, s1
	s_nop 0
	buffer_load_dwordx4 v35, s[36:39], s72 offen lds
	s_mov_b32 m0, s0
	v_readlane_b32 s1, v253, 11
	s_mov_b32 s0, m0
	s_mov_b32 m0, s1
	s_nop 0
	buffer_load_dwordx4 v32, s[36:39], s23 offen lds
	s_mov_b32 m0, s0
	v_lshlrev_b32_e32 v68, 3, v131
	s_mov_b32 s16, s33
	s_mov_b32 s33, s65
	s_mov_b32 s65, s97
	s_cmp_eq_u64 s[10:11], 0
	v_lshlrev_b32_e32 v160, 2, v68
	s_mov_b32 s0, 0x800000
	s_waitcnt vmcnt(7)
	v_lshlrev_b32_e32 v34, 16, v24
	v_and_b32_e32 v35, 0xffff0000, v24
	s_waitcnt vmcnt(5)
	v_lshlrev_b32_e32 v32, 16, v28
	v_and_b32_e32 v33, 0xffff0000, v28
	v_lshlrev_b32_e32 v36, 16, v25
	v_and_b32_e32 v37, 0xffff0000, v25
	v_lshlrev_b32_e32 v24, 16, v29
	v_and_b32_e32 v25, 0xffff0000, v29
	v_lshlrev_b32_e32 v38, 16, v26
	v_and_b32_e32 v39, 0xffff0000, v26
	v_lshlrev_b32_e32 v28, 16, v30
	v_and_b32_e32 v29, 0xffff0000, v30
	v_lshlrev_b32_e32 v40, 16, v27
	v_and_b32_e32 v41, 0xffff0000, v27
	v_lshlrev_b32_e32 v26, 16, v31
	v_and_b32_e32 v27, 0xffff0000, v31
	v_lshlrev_b32_e32 v42, 16, v16
	v_and_b32_e32 v43, 0xffff0000, v16
	s_waitcnt vmcnt(4)
	v_lshlrev_b32_e32 v30, 16, v20
	v_and_b32_e32 v31, 0xffff0000, v20
	v_lshlrev_b32_e32 v44, 16, v17
	v_and_b32_e32 v45, 0xffff0000, v17
	v_lshlrev_b32_e32 v16, 16, v21
	v_and_b32_e32 v17, 0xffff0000, v21
	v_lshlrev_b32_e32 v46, 16, v18
	v_and_b32_e32 v47, 0xffff0000, v18
	v_lshlrev_b32_e32 v20, 16, v22
	v_and_b32_e32 v21, 0xffff0000, v22
	v_lshlrev_b32_e32 v48, 16, v19
	v_and_b32_e32 v49, 0xffff0000, v19
	v_lshlrev_b32_e32 v18, 16, v23
	v_and_b32_e32 v19, 0xffff0000, v23
	s_waitcnt vmcnt(3)
	v_lshlrev_b32_e32 v50, 16, v8
	v_and_b32_e32 v51, 0xffff0000, v8
	s_waitcnt vmcnt(1)
	v_lshlrev_b32_e32 v22, 16, v12
	v_and_b32_e32 v23, 0xffff0000, v12
	v_lshlrev_b32_e32 v52, 16, v9
	v_and_b32_e32 v53, 0xffff0000, v9
	v_lshlrev_b32_e32 v8, 16, v13
	v_and_b32_e32 v9, 0xffff0000, v13
	v_lshlrev_b32_e32 v54, 16, v10
	v_and_b32_e32 v55, 0xffff0000, v10
	v_lshlrev_b32_e32 v12, 16, v14
	v_and_b32_e32 v13, 0xffff0000, v14
	v_lshlrev_b32_e32 v56, 16, v11
	v_and_b32_e32 v57, 0xffff0000, v11
	v_lshlrev_b32_e32 v10, 16, v15
	v_and_b32_e32 v11, 0xffff0000, v15
	v_lshlrev_b32_e32 v58, 16, v0
	v_and_b32_e32 v59, 0xffff0000, v0
	s_waitcnt vmcnt(0)
	v_lshlrev_b32_e32 v14, 16, v4
	v_and_b32_e32 v15, 0xffff0000, v4
	v_lshlrev_b32_e32 v60, 16, v1
	v_and_b32_e32 v61, 0xffff0000, v1
	v_lshlrev_b32_e32 v4, 16, v5
	v_and_b32_e32 v5, 0xffff0000, v5
	v_lshlrev_b32_e32 v64, 16, v2
	v_and_b32_e32 v65, 0xffff0000, v2
	v_lshlrev_b32_e32 v62, 16, v6
	v_and_b32_e32 v63, 0xffff0000, v6
	v_lshlrev_b32_e32 v66, 16, v3
	v_and_b32_e32 v67, 0xffff0000, v3
	v_lshlrev_b32_e32 v6, 16, v7
	v_and_b32_e32 v7, 0xffff0000, v7
	s_cbranch_scc1 .LBB0_499
	v_mul_f32_e32 v0, v35, v35
	v_pk_fma_f32 v[0:1], v[34:35], v[34:35], v[0:1] op_sel_hi:[1,1,0]
	v_mul_f32_e32 v2, v37, v37
	v_pk_fma_f32 v[0:1], v[36:37], v[36:37], v[0:1]
	v_lshl_add_u64 v[70:71], s[10:11], 0, v[160:161]
	v_pk_add_f32 v[0:1], v[2:3], v[0:1] op_sel_hi:[0,1]
	v_pk_fma_f32 v[0:1], v[38:39], v[38:39], v[0:1]
	v_mul_f32_e32 v2, v39, v39
	v_pk_add_f32 v[0:1], v[2:3], v[0:1] op_sel_hi:[0,1]
	v_pk_fma_f32 v[0:1], v[40:41], v[40:41], v[0:1]
	v_mul_f32_e32 v2, v41, v41
	v_pk_add_f32 v[0:1], v[2:3], v[0:1] op_sel_hi:[0,1]
	v_pk_fma_f32 v[0:1], v[42:43], v[42:43], v[0:1]
	v_mul_f32_e32 v2, v43, v43
	v_pk_add_f32 v[0:1], v[2:3], v[0:1] op_sel_hi:[0,1]
	v_pk_fma_f32 v[0:1], v[44:45], v[44:45], v[0:1]
	v_mul_f32_e32 v2, v45, v45
	v_pk_add_f32 v[0:1], v[2:3], v[0:1] op_sel_hi:[0,1]
	v_pk_fma_f32 v[0:1], v[46:47], v[46:47], v[0:1]
	v_mul_f32_e32 v2, v47, v47
	v_pk_add_f32 v[0:1], v[2:3], v[0:1] op_sel_hi:[0,1]
	v_pk_fma_f32 v[0:1], v[48:49], v[48:49], v[0:1]
	v_mul_f32_e32 v2, v49, v49
	v_pk_add_f32 v[0:1], v[2:3], v[0:1] op_sel_hi:[0,1]
	v_pk_fma_f32 v[0:1], v[32:33], v[32:33], v[0:1]
	v_mul_f32_e32 v2, v33, v33
	v_pk_add_f32 v[0:1], v[2:3], v[0:1] op_sel_hi:[0,1]
	v_pk_fma_f32 v[0:1], v[24:25], v[24:25], v[0:1]
	v_mul_f32_e32 v2, v25, v25
	v_pk_add_f32 v[0:1], v[2:3], v[0:1] op_sel_hi:[0,1]
	v_pk_fma_f32 v[0:1], v[28:29], v[28:29], v[0:1]
	v_mul_f32_e32 v2, v29, v29
	v_pk_add_f32 v[0:1], v[2:3], v[0:1] op_sel_hi:[0,1]
	v_pk_fma_f32 v[0:1], v[26:27], v[26:27], v[0:1]
	v_mul_f32_e32 v2, v27, v27
	v_pk_add_f32 v[0:1], v[2:3], v[0:1] op_sel_hi:[0,1]
	v_pk_fma_f32 v[0:1], v[30:31], v[30:31], v[0:1]
	v_mul_f32_e32 v2, v31, v31
	v_pk_add_f32 v[0:1], v[2:3], v[0:1] op_sel_hi:[0,1]
	v_pk_fma_f32 v[0:1], v[16:17], v[16:17], v[0:1]
	v_mul_f32_e32 v2, v17, v17
	v_pk_add_f32 v[0:1], v[2:3], v[0:1] op_sel_hi:[0,1]
	v_pk_fma_f32 v[0:1], v[20:21], v[20:21], v[0:1]
	v_mul_f32_e32 v2, v21, v21
	v_pk_add_f32 v[0:1], v[2:3], v[0:1] op_sel_hi:[0,1]
	v_pk_fma_f32 v[0:1], v[18:19], v[18:19], v[0:1]
	v_mul_f32_e32 v2, v19, v19
	v_pk_add_f32 v[0:1], v[2:3], v[0:1] op_sel_hi:[0,1]
	v_pk_fma_f32 v[0:1], v[50:51], v[50:51], v[0:1]
	v_mul_f32_e32 v2, v51, v51
	v_pk_add_f32 v[0:1], v[2:3], v[0:1] op_sel_hi:[0,1]
	v_pk_fma_f32 v[0:1], v[52:53], v[52:53], v[0:1]
	v_mul_f32_e32 v2, v53, v53
	v_pk_add_f32 v[0:1], v[2:3], v[0:1] op_sel_hi:[0,1]
	v_pk_fma_f32 v[0:1], v[54:55], v[54:55], v[0:1]
	v_mul_f32_e32 v2, v55, v55
	v_pk_add_f32 v[0:1], v[2:3], v[0:1] op_sel_hi:[0,1]
	v_pk_fma_f32 v[0:1], v[56:57], v[56:57], v[0:1]
	v_mul_f32_e32 v2, v57, v57
	v_pk_add_f32 v[0:1], v[2:3], v[0:1] op_sel_hi:[0,1]
	v_pk_fma_f32 v[0:1], v[58:59], v[58:59], v[0:1]
	v_mul_f32_e32 v2, v59, v59
	v_pk_add_f32 v[0:1], v[2:3], v[0:1] op_sel_hi:[0,1]
	v_pk_fma_f32 v[0:1], v[60:61], v[60:61], v[0:1]
	v_mul_f32_e32 v2, v61, v61
	v_pk_add_f32 v[0:1], v[2:3], v[0:1] op_sel_hi:[0,1]
	v_pk_fma_f32 v[0:1], v[64:65], v[64:65], v[0:1]
	v_mul_f32_e32 v2, v65, v65
	v_pk_add_f32 v[0:1], v[2:3], v[0:1] op_sel_hi:[0,1]
	v_pk_fma_f32 v[0:1], v[66:67], v[66:67], v[0:1]
	v_mul_f32_e32 v2, v67, v67
	v_pk_add_f32 v[0:1], v[2:3], v[0:1] op_sel_hi:[0,1]
	v_pk_fma_f32 v[0:1], v[22:23], v[22:23], v[0:1]
	v_mul_f32_e32 v2, v23, v23
	v_pk_add_f32 v[0:1], v[2:3], v[0:1] op_sel_hi:[0,1]
	v_pk_fma_f32 v[0:1], v[8:9], v[8:9], v[0:1]
	v_mul_f32_e32 v2, v9, v9
	v_pk_add_f32 v[0:1], v[2:3], v[0:1] op_sel_hi:[0,1]
	v_pk_fma_f32 v[0:1], v[12:13], v[12:13], v[0:1]
	v_mul_f32_e32 v2, v13, v13
	v_pk_add_f32 v[0:1], v[2:3], v[0:1] op_sel_hi:[0,1]
	v_pk_fma_f32 v[0:1], v[10:11], v[10:11], v[0:1]
	v_mul_f32_e32 v2, v11, v11
	v_pk_add_f32 v[0:1], v[2:3], v[0:1] op_sel_hi:[0,1]
	v_pk_fma_f32 v[0:1], v[14:15], v[14:15], v[0:1]
	v_mul_f32_e32 v2, v15, v15
	v_pk_add_f32 v[0:1], v[2:3], v[0:1] op_sel_hi:[0,1]
	v_pk_fma_f32 v[0:1], v[4:5], v[4:5], v[0:1]
	v_mul_f32_e32 v2, v5, v5
	v_pk_add_f32 v[0:1], v[2:3], v[0:1] op_sel_hi:[0,1]
	v_pk_fma_f32 v[0:1], v[62:63], v[62:63], v[0:1]
	v_mul_f32_e32 v2, v63, v63
	v_pk_add_f32 v[0:1], v[2:3], v[0:1] op_sel_hi:[0,1]
	v_pk_fma_f32 v[0:1], v[6:7], v[6:7], v[0:1]
	v_mul_f32_e32 v2, v7, v7
	v_pk_add_f32 v[0:1], v[2:3], v[0:1] op_sel_hi:[0,1]
	v_mov_b32_e32 v1, v0
	s_nop 1
	v_permlane32_swap_b32_e32 v0, v1
	v_add_f32_e32 v0, v0, v1
	v_fmamk_f32 v0, v0, 0x3c000000, v206
	v_cmp_gt_f32_e32 vcc, s0, v0
	v_mul_f32_e32 v1, 0x4b800000, v0
	s_nop 0
	v_cndmask_b32_e32 v0, v0, v1, vcc
	v_rsq_f32_e32 v0, v0
	s_nop 0
	v_mul_f32_e32 v1, 0x45800000, v0
	v_cndmask_b32_e32 v68, v0, v1, vcc
	v_mov_b64_e32 v[0:1], v[180:181]
	v_mov_b64_e32 v[2:3], v[182:183]
	s_waitcnt vmcnt(0) lgkmcnt(0)
	v_pk_mul_f32 v[2:3], v[68:69], v[2:3] op_sel_hi:[0,1]
	v_pk_mul_f32 v[0:1], v[68:69], v[0:1] op_sel_hi:[0,1]
	v_pk_mul_f32 v[48:49], v[2:3], v[48:49]
	v_pk_mul_f32 v[46:47], v[0:1], v[46:47]
	v_mov_b64_e32 v[0:1], v[184:185]
	v_mov_b64_e32 v[2:3], v[186:187]
	v_pk_mul_f32 v[2:3], v[68:69], v[2:3] op_sel_hi:[0,1]
	v_pk_mul_f32 v[0:1], v[68:69], v[0:1] op_sel_hi:[0,1]
	v_pk_mul_f32 v[44:45], v[2:3], v[44:45]
	v_pk_mul_f32 v[42:43], v[0:1], v[42:43]
	v_mov_b64_e32 v[0:1], v[188:189]
	v_mov_b64_e32 v[2:3], v[190:191]
	v_pk_mul_f32 v[2:3], v[2:3], v[68:69] op_sel_hi:[1,0]
	v_pk_mul_f32 v[0:1], v[0:1], v[68:69] op_sel_hi:[1,0]
	v_pk_mul_f32 v[40:41], v[2:3], v[40:41]
	v_pk_mul_f32 v[38:39], v[0:1], v[38:39]
	v_mov_b64_e32 v[0:1], v[192:193]
	v_mov_b64_e32 v[2:3], v[194:195]
	v_pk_mul_f32 v[2:3], v[2:3], v[68:69] op_sel_hi:[1,0]
	v_pk_mul_f32 v[0:1], v[0:1], v[68:69] op_sel_hi:[1,0]
	v_pk_mul_f32 v[36:37], v[2:3], v[36:37]
	v_pk_mul_f32 v[34:35], v[0:1], v[34:35]
	v_mov_b64_e32 v[0:1], v[196:197]
	v_mov_b64_e32 v[2:3], v[198:199]
	v_mov_b64_e32 v[76:77], v[200:201]
	v_mov_b64_e32 v[78:79], v[202:203]
	v_pk_mul_f32 v[0:1], v[68:69], v[0:1] op_sel_hi:[0,1]
	v_pk_mul_f32 v[76:77], v[68:69], v[76:77] op_sel_hi:[0,1]
	v_pk_mul_f32 v[32:33], v[76:77], v[32:33]
	v_pk_mul_f32 v[76:77], v[68:69], v[78:79] op_sel_hi:[0,1]
	v_pk_mul_f32 v[28:29], v[0:1], v[28:29]
	v_pk_mul_f32 v[0:1], v[68:69], v[2:3] op_sel_hi:[0,1]
	v_pk_mul_f32 v[24:25], v[76:77], v[24:25]
	v_pk_mul_f32 v[26:27], v[0:1], v[26:27]
	v_mov_b64_e32 v[0:1], v[208:209]
	v_mov_b64_e32 v[2:3], v[210:211]
	v_mov_b64_e32 v[76:77], v[216:217]
	v_mov_b64_e32 v[78:79], v[218:219]
	v_pk_mul_f32 v[0:1], v[68:69], v[0:1] op_sel_hi:[0,1]
	v_pk_mul_f32 v[76:77], v[68:69], v[76:77] op_sel_hi:[0,1]
	v_pk_mul_f32 v[30:31], v[76:77], v[30:31]
	v_pk_mul_f32 v[76:77], v[68:69], v[78:79] op_sel_hi:[0,1]
	v_pk_mul_f32 v[20:21], v[0:1], v[20:21]
	v_pk_mul_f32 v[0:1], v[68:69], v[2:3] op_sel_hi:[0,1]
	v_pk_mul_f32 v[16:17], v[76:77], v[16:17]
	v_pk_mul_f32 v[18:19], v[0:1], v[18:19]
	v_mov_b64_e32 v[0:1], v[220:221]
	v_mov_b64_e32 v[2:3], v[222:223]
	v_pk_mul_f32 v[2:3], v[68:69], v[2:3] op_sel_hi:[0,1]
	v_pk_mul_f32 v[0:1], v[68:69], v[0:1] op_sel_hi:[0,1]
	v_pk_mul_f32 v[66:67], v[2:3], v[66:67]
	v_pk_mul_f32 v[64:65], v[0:1], v[64:65]
	v_mov_b64_e32 v[0:1], v[224:225]
	v_mov_b64_e32 v[2:3], v[226:227]
	v_pk_mul_f32 v[2:3], v[68:69], v[2:3] op_sel_hi:[0,1]
	v_pk_mul_f32 v[0:1], v[68:69], v[0:1] op_sel_hi:[0,1]
	v_pk_mul_f32 v[60:61], v[2:3], v[60:61]
	v_pk_mul_f32 v[58:59], v[0:1], v[58:59]
	v_mov_b64_e32 v[0:1], v[228:229]
	v_mov_b64_e32 v[2:3], v[230:231]
	v_pk_mul_f32 v[2:3], v[68:69], v[2:3] op_sel_hi:[0,1]
	v_pk_mul_f32 v[0:1], v[68:69], v[0:1] op_sel_hi:[0,1]
	v_pk_mul_f32 v[56:57], v[2:3], v[56:57]
	v_pk_mul_f32 v[54:55], v[0:1], v[54:55]
	v_mov_b64_e32 v[0:1], v[232:233]
	v_mov_b64_e32 v[2:3], v[234:235]
	v_pk_mul_f32 v[2:3], v[68:69], v[2:3] op_sel_hi:[0,1]
	v_pk_mul_f32 v[0:1], v[68:69], v[0:1] op_sel_hi:[0,1]
	v_pk_mul_f32 v[52:53], v[2:3], v[52:53]
	v_pk_mul_f32 v[50:51], v[0:1], v[50:51]
	v_mov_b64_e32 v[0:1], v[236:237]
	v_mov_b64_e32 v[2:3], v[238:239]
	v_mov_b64_e32 v[76:77], v[240:241]
	v_mov_b64_e32 v[78:79], v[242:243]
	v_pk_mul_f32 v[0:1], v[68:69], v[0:1] op_sel_hi:[0,1]
	v_pk_mul_f32 v[76:77], v[68:69], v[76:77] op_sel_hi:[0,1]
	v_pk_mul_f32 v[22:23], v[76:77], v[22:23]
	v_pk_mul_f32 v[76:77], v[68:69], v[78:79] op_sel_hi:[0,1]
	v_pk_mul_f32 v[12:13], v[0:1], v[12:13]
	v_pk_mul_f32 v[0:1], v[68:69], v[2:3] op_sel_hi:[0,1]
	v_pk_mul_f32 v[8:9], v[76:77], v[8:9]
	v_pk_mul_f32 v[10:11], v[0:1], v[10:11]
	v_mov_b64_e32 v[0:1], v[244:245]
	v_mov_b64_e32 v[2:3], v[246:247]
	v_mov_b64_e32 v[76:77], v[248:249]
	v_mov_b64_e32 v[78:79], v[250:251]
	v_pk_mul_f32 v[0:1], v[68:69], v[0:1] op_sel_hi:[0,1]
	v_pk_mul_f32 v[70:71], v[68:69], v[76:77] op_sel_hi:[0,1]
	v_pk_mul_f32 v[14:15], v[70:71], v[14:15]
	v_pk_mul_f32 v[70:71], v[68:69], v[78:79] op_sel_hi:[0,1]
	v_pk_mul_f32 v[62:63], v[0:1], v[62:63]
	v_pk_mul_f32 v[0:1], v[68:69], v[2:3] op_sel_hi:[0,1]
	v_pk_mul_f32 v[4:5], v[70:71], v[4:5]
	v_pk_mul_f32 v[6:7], v[0:1], v[6:7]
